# v24 plus K-split of the phase-8 sample-row tiles (44 units, f32 atomic combine)
# baseline (speedup 1.0000x reference)
; template <class Epi, class Sched>
; __device__ __forceinline__ void gemm_phase(LAS unsigned char* lds, const int K, const Sched& S, const Epi& E) {
;     ...
;     f32x4 acc[2][2][4][2];
; #pragma unroll
;     for (int a = 0; a < 2; ++a)
; #pragma unroll
;         for (int b = 0; b < 2; ++b)
; #pragma unroll
;             for (int m = 0; m < 4; ++m)
; #pragma unroll
;                 for (int n = 0; n < 2; ++n) acc[a][b][m][n] = (f32x4){0.f, 0.f, 0.f, 0.f};
;     ...
;         for (int t = 0; t < nt; t += 2) {
;             const bool last = (t == nt - 2);
.LBB0_1446:
	s_add_u32 s48, s14, 0x100
	s_addc_u32 s49, s15, 0
	s_mov_b32 s50, -2
	s_cmp_lg_u32 s99, 0
	s_cselect_b32 s50, 38, s50
	v_mov_b64_e32 v[0:1], 0
	v_mov_b64_e32 v[2:3], 0
	v_mov_b64_e32 v[4:5], 0
	v_mov_b64_e32 v[6:7], 0
	v_mov_b64_e32 v[16:17], 0
	v_mov_b64_e32 v[18:19], 0
	v_mov_b64_e32 v[20:21], 0
	v_mov_b64_e32 v[22:23], 0
	v_mov_b64_e32 v[32:33], 0
	v_mov_b64_e32 v[34:35], 0
	v_mov_b64_e32 v[36:37], 0
	v_mov_b64_e32 v[38:39], 0
	v_mov_b64_e32 v[48:49], 0
	v_mov_b64_e32 v[50:51], 0
	v_mov_b64_e32 v[52:53], 0
	v_mov_b64_e32 v[54:55], 0
	v_mov_b64_e32 v[8:9], 0
	v_mov_b64_e32 v[10:11], 0
	v_mov_b64_e32 v[12:13], 0
	v_mov_b64_e32 v[14:15], 0
	v_mov_b64_e32 v[24:25], 0
	v_mov_b64_e32 v[26:27], 0
	v_mov_b64_e32 v[28:29], 0
	v_mov_b64_e32 v[30:31], 0
	v_mov_b64_e32 v[40:41], 0
	v_mov_b64_e32 v[42:43], 0
	v_mov_b64_e32 v[44:45], 0
	v_mov_b64_e32 v[46:47], 0
	v_mov_b64_e32 v[56:57], 0
	v_mov_b64_e32 v[58:59], 0
	v_mov_b64_e32 v[60:61], 0
	v_mov_b64_e32 v[62:63], 0
	s_waitcnt vmcnt(16)
	v_mov_b64_e32 v[64:65], 0
	v_mov_b64_e32 v[66:67], 0
	v_mov_b64_e32 v[68:69], 0
	v_mov_b64_e32 v[70:71], 0
	v_mov_b64_e32 v[80:81], 0
	v_mov_b64_e32 v[82:83], 0
	v_mov_b64_e32 v[84:85], 0
	v_mov_b64_e32 v[86:87], 0
	v_mov_b64_e32 v[96:97], 0
	v_mov_b64_e32 v[98:99], 0
	v_mov_b64_e32 v[100:101], 0
	v_mov_b64_e32 v[102:103], 0
	v_mov_b64_e32 v[112:113], 0
	v_mov_b64_e32 v[114:115], 0
	v_mov_b64_e32 v[116:117], 0
	v_mov_b64_e32 v[118:119], 0
	v_mov_b64_e32 v[72:73], 0
	v_mov_b64_e32 v[74:75], 0
	v_mov_b64_e32 v[76:77], 0
	v_mov_b64_e32 v[78:79], 0
	v_mov_b64_e32 v[88:89], 0
	v_mov_b64_e32 v[90:91], 0
	v_mov_b64_e32 v[92:93], 0
	v_mov_b64_e32 v[94:95], 0
	v_mov_b64_e32 v[104:105], 0
	v_mov_b64_e32 v[106:107], 0
	v_mov_b64_e32 v[108:109], 0
	v_mov_b64_e32 v[110:111], 0
	v_mov_b64_e32 v[120:121], 0
	v_mov_b64_e32 v[122:123], 0
	v_mov_b64_e32 v[124:125], 0
	v_mov_b64_e32 v[126:127], 0
	s_cmpk_eq_i32 s47, 0x100
	s_cselect_b64 vcc, -1, 0
